# attention step loop: softmax segment rewritten with packed f32 ops (pk bias add, exp2 argument as one pk fma x*log2e - m*log2e, pk sum tree, in-place bf16 pack); same math, ~100 fewer VALU per step
# speedup vs baseline: 1.0250x; 1.0051x over previous
; #define LAS __attribute__((address_space(3)))
; #define MFMA16(a, b, c) __builtin_amdgcn_mfma_f32_16x16x32_bf16((a), (b), (c), 0, 0, 0)
; __device__ __forceinline__ int att_fk(int key) { return ((key >> 3) & 3) + 4 * ((key >> 1) & 1); }
; __device__ __forceinline__ void attn_phase(const bf16_t* Q, const bf16_t* Kb, const bf16_t* VTa, const float* rpb, bf16_t* Y, LAS unsigned char* lds, int bx, int G, int tid, int wave, int lane) {
;     ...
; #pragma unroll
;             for (int ii = 0; ii < 4; ++ii) {
;                 const int i = 4 * hf + ii, dr = rs + i - r + 7;
;                 float bia[8];
; #pragma unroll
;                 for (int j = 0; j < 8; ++j) bia[j] = rl[((unsigned)(j - wlo) < (unsigned)wwd) ? dr * 31 + dci0 + j : 480];
; #pragma unroll
;                 for (int ta = 0; ta < 2; ++ta) {
;                     const int key = cs + 8 * (fr >> 2) + 4 * ta + (fr & 3), fk = att_fk(key);
;                     const LAS unsigned char* kp = KL + ((rs + i) & 7) * 8192 + key * 128;
;                     const bf16x8 kf0 = *(const LAS bf16x8*)(kp + ((fq ^ fk) << 4)), kf1 = *(const LAS bf16x8*)(kp + (((4 + fq) ^ fk) << 4));
;                     f32x4 a = {0.f, 0.f, 0.f, 0.f};
;                     a = MFMA16(kf0, qf0, a); a = MFMA16(kf1, qf1, a);
; #pragma unroll
;                     for (int idx = 0; idx < 4; ++idx) { a[idx] += bia[4 * ta + idx]; mx = fmaxf(mx, a[idx]); }
;                     s[ii][ta] = a;
;                 }
;             }
.LBB0_451:
	s_max_i32 s31, s94, 4
	s_add_i32 s31, s31, -4
	s_max_i32 s56, s94, 3
	s_min_u32 s64, s31, 0x78
	s_add_i32 s56, s56, -3
	s_add_i32 s58, s95, s64
	s_add_i32 s59, s20, s64
	s_min_u32 s80, s56, 0x78
	s_cmp_lg_u32 s80, s64
	s_cselect_b64 s[56:57], -1, 0
	s_add_i32 s59, s30, s59
	s_add_i32 s60, s64, s85
	s_mul_i32 s61, s59, 31
	s_add_i32 s74, s61, 0xffffff27
	s_lshl_b32 s59, s60, 13
	s_and_b32 s75, s59, 0xe000
	v_add_u32_e32 v10, s74, v46
	s_waitcnt vmcnt(1)
	v_lshl_add_u32 v190, v10, 2, s84
	v_cndmask_b32_e64 v11, v194, v190, s[40:41]
	v_add_u32_e32 v14, s75, v61
	s_waitcnt lgkmcnt(0)
	s_barrier
	v_add_u32_e32 v19, v14, v55
	ds_read_b32 v202, v11
	v_add_u32_e32 v18, v14, v41
	ds_read_b128 v[14:17], v19
	v_cndmask_b32_e64 v11, v195, v190, s[42:43]
	ds_read_b32 v203, v11 offset:4
	v_cndmask_b32_e64 v11, v196, v190, s[44:45]
	ds_read_b32 v204, v11 offset:8
	v_cndmask_b32_e64 v11, v197, v190, s[46:47]
	ds_read_b32 v205, v11 offset:12
	v_cndmask_b32_e64 v11, v198, v190, s[48:49]
	ds_read_b32 v206, v11 offset:16
	v_cndmask_b32_e64 v11, v199, v190, s[50:51]
	ds_read_b32 v207, v11 offset:20
	v_cndmask_b32_e64 v11, v200, v190, s[52:53]
	v_cndmask_b32_e64 v10, v201, v190, s[54:55]
	ds_read_b32 v208, v11 offset:24
	ds_read_b32 v209, v10 offset:28
	ds_read_b128 v[10:13], v18
	s_waitcnt vmcnt(0) lgkmcnt(0)
	v_mfma_f32_16x16x32_bf16 v[10:13], v[10:13], v[6:9], 0
	s_add_i32 s59, s64, s89
	s_add_i32 vcc_hi, s61, 0xffffff46
	s_lshl_b32 s59, s59, 13
	v_mfma_f32_16x16x32_bf16 v[10:13], v[14:17], v[2:5], v[10:13]
	ds_read_b128 v[14:17], v18 offset:512
	ds_read_b128 v[18:21], v19 offset:512
	s_and_b32 vcc_lo, s59, 0xe000
	v_add_u32_e32 v22, vcc_lo, v61
	s_waitcnt lgkmcnt(1)
	v_mfma_f32_16x16x32_bf16 v[14:17], v[14:17], v[6:9], 0
	v_add_u32_e32 v27, v22, v55
	v_add_u32_e32 v26, v22, v41
	ds_read_b128 v[22:25], v27
	s_waitcnt lgkmcnt(1)
	v_mfma_f32_16x16x32_bf16 v[14:17], v[18:21], v[2:5], v[14:17]
	v_add_u32_e32 v18, vcc_hi, v46
	v_lshl_add_u32 v191, v18, 2, s84
	v_cndmask_b32_e64 v19, v194, v191, s[40:41]
	ds_read_b32 v210, v19
	v_cndmask_b32_e64 v19, v195, v191, s[42:43]
	ds_read_b32 v211, v19 offset:4
	v_cndmask_b32_e64 v19, v196, v191, s[44:45]
	ds_read_b32 v212, v19 offset:8
	v_cndmask_b32_e64 v19, v197, v191, s[46:47]
	ds_read_b32 v213, v19 offset:12
	v_cndmask_b32_e64 v19, v198, v191, s[48:49]
	ds_read_b32 v214, v19 offset:16
	v_cndmask_b32_e64 v19, v199, v191, s[50:51]
	ds_read_b32 v215, v19 offset:20
	v_cndmask_b32_e64 v19, v200, v191, s[52:53]
	v_cndmask_b32_e64 v18, v201, v191, s[54:55]
	ds_read_b32 v216, v19 offset:24
	ds_read_b32 v217, v18 offset:28
	ds_read_b128 v[18:21], v26
	s_waitcnt lgkmcnt(0)
	v_mfma_f32_16x16x32_bf16 v[18:21], v[18:21], v[6:9], 0
	s_add_i32 s59, s64, s90
	s_addk_i32 s61, 0xff65
	s_lshl_b32 s59, s59, 13
	v_mfma_f32_16x16x32_bf16 v[18:21], v[22:25], v[2:5], v[18:21]
	ds_read_b128 v[22:25], v26 offset:512
	ds_read_b128 v[26:29], v27 offset:512
	s_and_b32 s60, s59, 0xe000
	v_add_u32_e32 v30, s60, v61
	s_waitcnt lgkmcnt(1)
	v_mfma_f32_16x16x32_bf16 v[22:25], v[22:25], v[6:9], 0
	v_add_u32_e32 v35, v30, v55
	v_add_u32_e32 v34, v30, v41
	ds_read_b128 v[30:33], v35
	s_waitcnt lgkmcnt(1)
	v_mfma_f32_16x16x32_bf16 v[22:25], v[26:29], v[2:5], v[22:25]
	v_add_u32_e32 v26, s61, v46
	v_lshl_add_u32 v192, v26, 2, s84
	v_cndmask_b32_e64 v27, v194, v192, s[40:41]
	ds_read_b32 v102, v27
	v_cndmask_b32_e64 v27, v195, v192, s[42:43]
	ds_read_b32 v103, v27 offset:4
	v_cndmask_b32_e64 v27, v196, v192, s[44:45]
	ds_read_b32 v104, v27 offset:8
	v_cndmask_b32_e64 v27, v197, v192, s[46:47]
	ds_read_b32 v105, v27 offset:12
	v_cndmask_b32_e64 v27, v198, v192, s[48:49]
	ds_read_b32 v106, v27 offset:16
	v_cndmask_b32_e64 v27, v199, v192, s[50:51]
	ds_read_b32 v107, v27 offset:20
	v_cndmask_b32_e64 v27, v200, v192, s[52:53]
	v_cndmask_b32_e64 v26, v201, v192, s[54:55]
	ds_read_b32 v108, v27 offset:24
	ds_read_b32 v109, v26 offset:28
	ds_read_b128 v[26:29], v34
	s_waitcnt lgkmcnt(0)
	v_mfma_f32_16x16x32_bf16 v[26:29], v[26:29], v[6:9], 0
	s_add_i32 s58, s30, s58
	s_add_i32 s31, s64, s91
	s_mul_i32 s59, s58, 31
	v_mfma_f32_16x16x32_bf16 v[26:29], v[30:33], v[2:5], v[26:29]
	ds_read_b128 v[30:33], v34 offset:512
	ds_read_b128 v[34:37], v35 offset:512
	s_addk_i32 s59, 0xff27
	s_lshl_b32 s31, s31, 13
	s_waitcnt lgkmcnt(1)
	v_mfma_f32_16x16x32_bf16 v[30:33], v[30:33], v[6:9], 0
	s_and_b32 s58, s31, 0xe000
	v_add_u32_e32 v118, s58, v61
	v_add_u32_e32 v123, v118, v55
	s_waitcnt lgkmcnt(0)
	v_mfma_f32_16x16x32_bf16 v[30:33], v[34:37], v[2:5], v[30:33]
	v_add_u32_e32 v34, s59, v46
	v_lshl_add_u32 v193, v34, 2, s84
	v_cndmask_b32_e64 v35, v194, v193, s[40:41]
	ds_read_b32 v110, v35
	v_add_u32_e32 v122, v118, v41
	ds_read_b128 v[118:121], v123
	v_cndmask_b32_e64 v35, v195, v193, s[42:43]
	ds_read_b32 v111, v35 offset:4
	v_cndmask_b32_e64 v35, v196, v193, s[44:45]
	ds_read_b32 v112, v35 offset:8
	v_cndmask_b32_e64 v35, v197, v193, s[46:47]
	ds_read_b32 v113, v35 offset:12
	v_cndmask_b32_e64 v35, v198, v193, s[48:49]
	ds_read_b32 v114, v35 offset:16
	v_cndmask_b32_e64 v35, v199, v193, s[50:51]
	ds_read_b32 v115, v35 offset:20
	v_cndmask_b32_e64 v35, v200, v193, s[52:53]
	v_cndmask_b32_e64 v34, v201, v193, s[54:55]
	ds_read_b32 v116, v35 offset:24
	ds_read_b32 v117, v34 offset:28
	ds_read_b128 v[34:37], v122
	s_waitcnt lgkmcnt(0)
	v_mfma_f32_16x16x32_bf16 v[34:37], v[34:37], v[6:9], 0
	s_cmp_eq_u32 s80, s64
	v_mfma_f32_16x16x32_bf16 v[34:37], v[118:121], v[2:5], v[34:37]
	ds_read_b128 v[118:121], v122 offset:512
	ds_read_b128 v[122:125], v123 offset:512
	s_waitcnt lgkmcnt(0)
	s_barrier
	s_waitcnt lgkmcnt(1)
	v_mfma_f32_16x16x32_bf16 v[6:9], v[118:121], v[6:9], 0
	s_waitcnt lgkmcnt(0)
	v_mfma_f32_16x16x32_bf16 v[2:5], v[122:125], v[2:5], v[6:9]
	s_cbranch_scc1 .LBB0_453
	s_lshl_b32 s31, s64, 17
	s_add_u32 s58, s21, s31
	s_addc_u32 s59, s83, 0
	s_nop 1
	v_lshl_add_u64 v[6:7], s[58:59], 0, v[50:51]
	v_lshl_add_u64 v[6:7], v[6:7], 0, s[22:23]
	s_lshl_b32 s31, s64, 13
	v_lshl_add_u64 v[6:7], v[6:7], 0, v[0:1]
	s_mov_b64 s[58:59], 0x100000
	s_and_b32 s31, s31, 0xe000
	v_lshl_add_u64 v[6:7], v[6:7], 0, s[58:59]
	s_add_i32 m0, s86, s31
	s_nop 0
	global_load_lds_dwordx4 v[6:7], off
; __device__ __forceinline__ float fast_exp2(float x) { return __builtin_amdgcn_exp2f(x); }
; __device__ __forceinline__ u32x4 pack8(f32x4 a, f32x4 b) { u32x4 w; w.x = cvt_pk_bf16(a[0], a[1]); w.y = cvt_pk_bf16(a[2], a[3]); w.z = cvt_pk_bf16(b[0], b[1]); w.w = cvt_pk_bf16(b[2], b[3]); return w; }
; #define SCHED_FENCE() __builtin_amdgcn_sched_barrier(0)
; __device__ __forceinline__ void attn_phase(const bf16_t* Q, const bf16_t* Kb, const bf16_t* VTa, const float* rpb, bf16_t* Y, LAS unsigned char* lds, int bx, int G, int tid, int wave, int lane) {
;     ...
;             if (has_next) { const bf16_t* qp = Q + (size_t)((r + 1) * 64 + c) * 1024 + h * 64 + 8 * fq; qf0 = *(const bf16x8*)qp; qf1 = *(const bf16x8*)(qp + 32); }
;             SCHED_FENCE();
;             mx = fmaxf(mx, __shfl_xor(mx, 16)); mx = fmaxf(mx, __shfl_xor(mx, 32));
;             float l = 0.f;
;             bf16x8 pb[4];
; #pragma unroll
;             for (int ii = 0; ii < 4; ++ii) {
;                 f32x4 p0, p1;
; #pragma unroll
;                 for (int idx = 0; idx < 4; ++idx) { p0[idx] = fast_exp2((s[ii][0][idx] - mx) * 1.4426950409f); p1[idx] = fast_exp2((s[ii][1][idx] - mx) * 1.4426950409f); }
;                 l += (p0[0] + p0[1]) + (p0[2] + p0[3]) + (p1[0] + p1[1]) + (p1[2] + p1[3]);
;                 const u32x4 pw = pack8(p0, p1); pb[ii] = __builtin_bit_cast(bf16x8, pw);
;             }
;             l += __shfl_xor(l, 16); l += __shfl_xor(l, 32);
;             SCHED_FENCE();
;             if (newrow) asm volatile("s_waitcnt vmcnt(3)" ::: "memory"); else if (has_next) asm volatile("s_waitcnt vmcnt(2)" ::: "memory"); else asm volatile("s_waitcnt vmcnt(0)" ::: "memory");
.LBB0_453:
	v_pk_add_f32 v[10:11], v[10:11], v[202:203]
	v_pk_add_f32 v[12:13], v[12:13], v[204:205]
	v_pk_add_f32 v[14:15], v[14:15], v[206:207]
	v_pk_add_f32 v[16:17], v[16:17], v[208:209]
	v_pk_add_f32 v[18:19], v[18:19], v[210:211]
	v_pk_add_f32 v[20:21], v[20:21], v[212:213]
	v_pk_add_f32 v[22:23], v[22:23], v[214:215]
	v_pk_add_f32 v[24:25], v[24:25], v[216:217]
	v_pk_add_f32 v[26:27], v[26:27], v[102:103]
	v_pk_add_f32 v[28:29], v[28:29], v[104:105]
	v_pk_add_f32 v[30:31], v[30:31], v[106:107]
	v_pk_add_f32 v[32:33], v[32:33], v[108:109]
	v_pk_add_f32 v[34:35], v[34:35], v[110:111]
	v_pk_add_f32 v[36:37], v[36:37], v[112:113]
	v_pk_add_f32 v[224:225], v[2:3], v[114:115]
	v_pk_add_f32 v[226:227], v[4:5], v[116:117]
	v_max3_f32 v221, v10, s6, v11
	v_max3_f32 v221, v221, v12, v13
	v_max3_f32 v221, v221, v14, v15
	v_max3_f32 v221, v221, v16, v17
	v_max3_f32 v221, v221, v18, v19
	v_max3_f32 v221, v221, v20, v21
	v_max3_f32 v221, v221, v22, v23
	v_max3_f32 v221, v221, v24, v25
	v_max3_f32 v221, v221, v26, v27
	v_max3_f32 v221, v221, v28, v29
	v_max3_f32 v221, v221, v30, v31
	v_max3_f32 v221, v221, v32, v33
	v_max3_f32 v221, v221, v34, v35
	v_max3_f32 v221, v221, v36, v37
	v_max3_f32 v221, v221, v224, v225
	v_max3_f32 v221, v221, v226, v227
	v_add_u32_e32 v230, 64, v98
	v_ashrrev_i32_e32 v231, 31, v230
	v_lshlrev_b64 v[228:229], 11, v[230:231]
	v_lshl_add_u64 v[228:229], v[92:93], 0, v[228:229]
	global_load_dwordx4 v[6:9], v[228:229], off
	s_nop 0
	global_load_dwordx4 v[2:5], v[228:229], off offset:64
	v_and_b32_e32 v239, 64, v241
	v_xor_b32_e32 v238, 16, v241
	v_add_u32_e32 v239, 64, v239
	v_cmp_lt_i32_e32 vcc, v238, v239
	v_xor_b32_e32 v246, 32, v241
	s_nop 0
	v_cndmask_b32_e32 v238, v241, v238, vcc
	v_lshlrev_b32_e32 v238, 2, v238
	ds_bpermute_b32 v247, v238, v221
	v_cmp_lt_i32_e32 vcc, v246, v239
	v_mov_b32_e32 v248, 0x3fb8aa3b
	s_waitcnt lgkmcnt(0)
	v_max_f32_e32 v247, v247, v247
	v_cndmask_b32_e32 v239, v241, v246, vcc
	v_max_f32_e32 v221, v221, v247
	v_lshlrev_b32_e32 v239, 2, v239
	ds_bpermute_b32 v247, v239, v221
	s_waitcnt lgkmcnt(0)
	v_max_f32_e32 v247, v247, v247
	v_max_f32_e32 v221, v221, v247
	v_mul_f32_e32 v222, 0xbfb8aa3b, v221
	v_pk_fma_f32 v[10:11], v[10:11], v[248:249], v[222:223] op_sel_hi:[1,0,0]
	v_pk_fma_f32 v[12:13], v[12:13], v[248:249], v[222:223] op_sel_hi:[1,0,0]
	v_pk_fma_f32 v[14:15], v[14:15], v[248:249], v[222:223] op_sel_hi:[1,0,0]
	v_pk_fma_f32 v[16:17], v[16:17], v[248:249], v[222:223] op_sel_hi:[1,0,0]
	v_pk_fma_f32 v[18:19], v[18:19], v[248:249], v[222:223] op_sel_hi:[1,0,0]
	v_pk_fma_f32 v[20:21], v[20:21], v[248:249], v[222:223] op_sel_hi:[1,0,0]
	v_pk_fma_f32 v[22:23], v[22:23], v[248:249], v[222:223] op_sel_hi:[1,0,0]
	v_pk_fma_f32 v[24:25], v[24:25], v[248:249], v[222:223] op_sel_hi:[1,0,0]
	v_pk_fma_f32 v[26:27], v[26:27], v[248:249], v[222:223] op_sel_hi:[1,0,0]
	v_pk_fma_f32 v[28:29], v[28:29], v[248:249], v[222:223] op_sel_hi:[1,0,0]
	v_pk_fma_f32 v[30:31], v[30:31], v[248:249], v[222:223] op_sel_hi:[1,0,0]
	v_pk_fma_f32 v[32:33], v[32:33], v[248:249], v[222:223] op_sel_hi:[1,0,0]
	v_pk_fma_f32 v[34:35], v[34:35], v[248:249], v[222:223] op_sel_hi:[1,0,0]
	v_pk_fma_f32 v[36:37], v[36:37], v[248:249], v[222:223] op_sel_hi:[1,0,0]
	v_pk_fma_f32 v[224:225], v[224:225], v[248:249], v[222:223] op_sel_hi:[1,0,0]
	v_pk_fma_f32 v[226:227], v[226:227], v[248:249], v[222:223] op_sel_hi:[1,0,0]
	v_exp_f32_e32 v10, v10
	v_exp_f32_e32 v11, v11
	v_exp_f32_e32 v12, v12
	v_exp_f32_e32 v13, v13
	v_exp_f32_e32 v14, v14
	v_exp_f32_e32 v15, v15
	v_exp_f32_e32 v16, v16
	v_exp_f32_e32 v17, v17
	v_exp_f32_e32 v18, v18
	v_exp_f32_e32 v19, v19
	v_exp_f32_e32 v20, v20
	v_exp_f32_e32 v21, v21
	v_exp_f32_e32 v22, v22
	v_exp_f32_e32 v23, v23
	v_exp_f32_e32 v24, v24
	v_exp_f32_e32 v25, v25
	v_exp_f32_e32 v26, v26
	v_exp_f32_e32 v27, v27
	v_exp_f32_e32 v28, v28
	v_exp_f32_e32 v29, v29
	v_exp_f32_e32 v30, v30
	v_exp_f32_e32 v31, v31
	v_exp_f32_e32 v32, v32
	v_exp_f32_e32 v33, v33
	v_exp_f32_e32 v34, v34
	v_exp_f32_e32 v35, v35
	v_exp_f32_e32 v36, v36
	v_exp_f32_e32 v37, v37
	v_exp_f32_e32 v224, v224
	v_exp_f32_e32 v225, v225
	v_exp_f32_e32 v226, v226
	v_exp_f32_e32 v227, v227
	v_pk_add_f32 v[250:251], v[10:11], v[12:13]
	v_pk_add_f32 v[252:253], v[14:15], v[16:17]
	v_pk_add_f32 v[246:247], v[18:19], v[20:21]
	v_pk_add_f32 v[250:251], v[250:251], v[246:247]
	v_pk_add_f32 v[246:247], v[22:23], v[24:25]
	v_pk_add_f32 v[252:253], v[252:253], v[246:247]
	v_pk_add_f32 v[246:247], v[26:27], v[28:29]
	v_pk_add_f32 v[250:251], v[250:251], v[246:247]
	v_pk_add_f32 v[246:247], v[30:31], v[32:33]
	v_pk_add_f32 v[252:253], v[252:253], v[246:247]
	v_pk_add_f32 v[246:247], v[34:35], v[36:37]
	v_pk_add_f32 v[250:251], v[250:251], v[246:247]
	v_pk_add_f32 v[246:247], v[224:225], v[226:227]
	v_pk_add_f32 v[252:253], v[252:253], v[246:247]
	v_pk_add_f32 v[250:251], v[250:251], v[252:253]
	v_cvt_pk_bf16_f32 v10, v10, v11
	v_cvt_pk_bf16_f32 v11, v12, v13
	v_cvt_pk_bf16_f32 v12, v14, v15
	v_cvt_pk_bf16_f32 v13, v16, v17
	v_cvt_pk_bf16_f32 v14, v18, v19
	v_cvt_pk_bf16_f32 v15, v20, v21
	v_cvt_pk_bf16_f32 v16, v22, v23
	v_cvt_pk_bf16_f32 v17, v24, v25
	v_cvt_pk_bf16_f32 v18, v26, v27
	v_cvt_pk_bf16_f32 v19, v28, v29
	v_cvt_pk_bf16_f32 v20, v30, v31
	v_cvt_pk_bf16_f32 v21, v32, v33
	v_cvt_pk_bf16_f32 v26, v34, v35
	v_cvt_pk_bf16_f32 v27, v36, v37
	v_cvt_pk_bf16_f32 v28, v224, v225
	v_cvt_pk_bf16_f32 v29, v226, v227
	v_add_f32_e32 v22, v250, v251
	v_mov_b32_e32 v32, v221
	ds_bpermute_b32 v247, v238, v22
	v_mov_b32_e32 v30, v230
	v_mov_b32_e32 v31, v238
	v_mov_b32_e32 v34, v239
	s_waitcnt lgkmcnt(0)
	v_add_f32_e32 v22, v22, v247
	ds_bpermute_b32 v23, v239, v22
	v_cndmask_b32_e64 v24, 0, 1, s[56:57]
	v_cmp_ne_u32_e64 s[60:61], 1, v24
	s_andn2_b64 vcc, exec, s[56:57]
	s_mov_b64 s[56:57], -1
	s_cbranch_vccnz .LBB0_455
	s_waitcnt vmcnt(3)
	s_mov_b64 s[56:57], 0
